# spatial phase: previous tile's 8 Y stores may stay outstanding across the tile boundary (counted vmcnt(8))
# baseline (speedup 1.0000x reference)
; #define LAS __attribute__((address_space(3)))
; __device__ __forceinline__ int tid_opaque() { int t = threadIdx.x; asm volatile("" : "+v"(t)); return t; }
; __device__ __forceinline__ int sgpr_opaque(int x) { asm volatile("" : "+s"(x)); return x; }
; #define INP(i) ((const float*)ldp(T, (i)))
; __device__ __forceinline__ void spatial_phase(const PT& T, int a, LAS unsigned char* lds, int vc) {
;     const int tid = tid_opaque(), lane = tid & 63, wid = __builtin_amdgcn_readfirstlane(tid >> 6), fr = lane & 15, fq = lane >> 4;
;     const bf16_t* __restrict__ Z = (const bf16_t*)((unsigned char*)OUTP); bf16_t* __restrict__ Y = (bf16_t*)(WSP + WS_T2);
;     const float* __restrict__ vst = (const float*)(WSP + WS_VST + (size_t)a * MiB);
;     const float* __restrict__ gv = INP(5) + a * D; const float* __restrict__ bs = INP(7) + a * D;
;     const bf16_t* __restrict__ Wm = (const bf16_t*)(WSP + WS_W) + WO_A_S0 + (size_t)a * WO_A_STRIDE;
;     constexpr int LDW = 136;
;     LAS bf16_t* sW = (LAS bf16_t*)lds; LAS bf16_t* sV = (LAS bf16_t*)(lds + 128 * LDW * 2);
;     const int R8 = sgpr_opaque(gridDim.x) >> 3, vx = sgpr_opaque(vc) & 7, vr = sgpr_opaque(vc) >> 3;
;     const int wi = wid >> 2, wc = wid & 3, ib = wi * 64, cb = wc * 32;
;     const int jq = tid >> 4, c8 = (tid & 15) * 8;
;     for (int ti = vr; ti < 256; ti += R8) {
;         const int t = 256 * vx + ti, nb = t >> 3, g = t & 7;
;         u32x4 wreg[4], vreg[4]; f32x4 p1[4], p2[4];
; #pragma unroll
;         for (int q = 0; q < 4; ++q) { const int j = jq + 32 * q; const size_t row = (size_t)nb * 128 + j;
;             wreg[q] = *(const u32x4*)(Wm + (size_t)g * 16384 + j * 128 + c8);
;             vreg[q] = *(const u32x4*)(Z + row * 2048 + 1024 + g * 128 + c8);
;             p1[q] = *(const f32x4*)(vst + 8 * row); p2[q] = *(const f32x4*)(vst + 8 * row + 4); }
;         const f32x4 g0 = *(const f32x4*)(gv + g * 128 + c8), g1 = *(const f32x4*)(gv + g * 128 + c8 + 4);
.LBB0_795:
	v_readlane_b32 s0, v254, 8
	v_mov_b32_e32 v0, v220
	v_readlane_b32 s4, v254, 13
	v_mov_b32_e32 v2, s0
	s_waitcnt lgkmcnt(0)
	ds_read2_b64 v[2:5], v2 offset1:1
	v_readlane_b32 s0, v254, 12
	s_mov_b32 s15, s68
	v_readfirstlane_b32 s10, v0
	v_mov_b32_e32 v6, s0
	ds_read_b64 v[6:7], v6
	s_waitcnt lgkmcnt(0)
	v_readfirstlane_b32 s0, v2
	v_mov_b32_e32 v2, s4
	v_readfirstlane_b32 s1, v3
	ds_read_b64 v[2:3], v2
	v_readlane_b32 s4, v254, 22
	s_mov_b32 s18, s4
	s_ashr_i32 s4, s4, 3
	v_readfirstlane_b32 s16, v5
	v_readfirstlane_b32 s19, v4
	v_readfirstlane_b32 s11, v7
	v_readfirstlane_b32 s17, v6
	s_waitcnt lgkmcnt(0)
	v_readfirstlane_b32 s9, v3
	s_cmpk_gt_i32 s4, 0xff
	v_readfirstlane_b32 s8, v2
	s_cbranch_scc1 .LBB0_800
	s_add_u32 s5, s19, 0x15000000
	v_readlane_b32 s6, v254, 27
	s_addc_u32 s14, s16, 0
	v_readlane_b32 s7, v254, 28
	s_mov_b32 s28, s6
	s_ashr_i32 s29, s6, 31
	s_lshl_b64 s[6:7], s[28:29], 20
	s_add_u32 s6, s19, s6
	s_addc_u32 s7, s16, s7
	s_add_u32 s6, s6, 0x19500000
	s_addc_u32 s7, s7, 0
	s_lshl_b32 s20, s28, 10
	s_ashr_i32 s21, s20, 31
	s_lshl_b64 s[20:21], s[20:21], 2
	s_add_u32 s8, s8, s20
	s_addc_u32 s9, s9, s21
	s_lshr_b32 s22, s10, 1
	s_ashr_i32 s25, s10, 2
	s_ashr_i32 s15, s15, 3
	s_and_b32 s24, s22, 0x60
	s_and_b32 s26, s25, 0xffffffc0
	s_mul_i32 s22, s28, 0x640000
	s_mul_hi_i32 s23, s28, 0x640000
	s_add_u32 s22, s19, s22
	s_addc_u32 s23, s16, s23
	s_add_u32 s20, s17, s20
	s_addc_u32 s21, s11, s21
	s_lshl_b32 s11, s18, 8
	v_lshlrev_b32_e32 v2, 3, v0
	s_and_b32 s16, s11, 0x700
	v_ashrrev_i32_e32 v34, 4, v0
	v_and_b32_e32 v2, 0x78, v2
	s_cmpk_lt_u32 s10, 0x100
	s_movk_i32 s11, 0x110
	v_bfe_u32 v3, v0, 4, 2
	v_and_b32_e32 v12, 15, v0
	v_lshlrev_b32_e32 v0, 1, v2
	s_cselect_b32 s17, 2, 4
	v_mul_lo_u32 v6, v34, s11
	s_and_b32 s10, s10, 0xc0
	v_lshl_add_u64 v[4:5], s[22:23], 0, v[0:1]
	v_add3_u32 v91, 0, v0, v6
	v_mov_b32_e32 v0, s10
	s_movk_i32 s10, 0x880
	v_or_b32_e32 v40, s26, v12
	v_mad_u32_u24 v0, v3, s10, v0
	v_ashrrev_i32_e32 v41, 31, v40
	v_lshl_or_b32 v0, v12, 1, v0
	v_readlane_b32 s10, v254, 14
	v_lshlrev_b64 v[56:57], 12, v[40:41]
	v_lshlrev_b64 v[64:65], 11, v[40:41]
	v_add_u32_e32 v41, s10, v0
	s_lshr_b32 s10, s25, 6
	s_mov_b64 s[18:19], 0xa00000
	s_mulk_i32 s10, 0x4400
	v_lshl_add_u64 v[36:37], v[4:5], 0, s[18:19]
	v_lshlrev_b32_e32 v4, 2, v2
	v_mov_b32_e32 v5, v1
	v_add_u32_e32 v44, 32, v34
	v_add_u32_e32 v48, 64, v34
	v_add_u32_e32 v52, 0x60, v34
	v_or_b32_e32 v6, 16, v40
	v_or_b32_e32 v8, 32, v40
	v_or_b32_e32 v10, 48, v40
	v_mov_b32_e32 v0, s10
	v_lshl_add_u64 v[38:39], s[20:21], 0, v[4:5]
	v_lshlrev_b32_e32 v4, 2, v3
	v_lshlrev_b32_e32 v5, 4, v3
	v_lshlrev_b32_e32 v42, 7, v34
	v_lshlrev_b32_e32 v46, 7, v44
	v_lshlrev_b32_e32 v50, 7, v48
	v_lshlrev_b32_e32 v54, 7, v52
	v_ashrrev_i32_e32 v7, 31, v6
	v_ashrrev_i32_e32 v9, 31, v8
	v_ashrrev_i32_e32 v11, 31, v10
	v_mad_u32_u24 v0, v12, s11, v0
	v_or_b32_e32 v90, s24, v4
	v_ashrrev_i32_e32 v35, 31, v34
	v_ashrrev_i32_e32 v43, 31, v42
	v_ashrrev_i32_e32 v45, 31, v44
	v_ashrrev_i32_e32 v47, 31, v46
	v_ashrrev_i32_e32 v49, 31, v48
	v_ashrrev_i32_e32 v51, 31, v50
	v_ashrrev_i32_e32 v53, 31, v52
	v_ashrrev_i32_e32 v55, 31, v54
	v_lshlrev_b64 v[58:59], 12, v[6:7]
	v_lshlrev_b64 v[60:61], 12, v[8:9]
	v_lshlrev_b64 v[62:63], 12, v[10:11]
	v_lshlrev_b64 v[66:67], 11, v[6:7]
	v_lshlrev_b64 v[68:69], 11, v[8:9]
	v_lshlrev_b64 v[70:71], 11, v[10:11]
	v_add3_u32 v92, v0, v5, 0
	v_lshlrev_b32_e32 v0, 1, v2
	s_lshl_b32 s18, s24, 1
	v_lshlrev_b32_e32 v72, 1, v4
	s_add_i32 s10, s4, s16
	s_ashr_i32 s10, s10, 3
	s_ashr_i32 s11, s10, 31
	s_lshl_b64 s[20:21], s[10:11], 7
	v_lshl_add_u64 v[120:121], s[20:21], 0, v[34:35]
	v_lshlrev_b64 v[122:123], 5, v[120:121]
	v_lshl_add_u64 v[122:123], s[6:7], 0, v[122:123]
	global_load_dwordx4 v[140:143], v[122:123], off
	global_load_dwordx4 v[144:147], v[122:123], off offset:16
	s_and_b32 s19, s4, 7
	s_lshl_b32 s46, s19, 15
	v_lshlrev_b64 v[120:121], 12, v[120:121]
	v_lshl_add_u64 v[124:125], v[36:37], 0, s[46:47]
	v_lshl_add_u64 v[120:121], s[0:1], 0, v[120:121]
	s_lshl_b32 s46, s19, 8
	v_lshl_add_u64 v[120:121], v[120:121], 0, s[46:47]
	v_lshl_add_u64 v[120:121], v[120:121], 0, v[0:1]
	global_load_dwordx4 v[148:151], v[120:121], off offset:2048
	s_mov_b32 s23, s47
	s_lshl_b32 s22, s19, 9
	v_lshl_add_u64 v[120:121], v[38:39], 0, s[22:23]
	global_load_dwordx4 v[128:131], v[120:121], off
	s_nop 0
	global_load_dwordx4 v[120:123], v[120:121], off offset:16
	v_lshl_add_u64 v[126:127], v[42:43], 1, v[124:125]
	v_lshl_add_u64 v[132:133], v[46:47], 1, v[124:125]
	v_lshl_add_u64 v[168:169], s[20:21], 0, v[44:45]
	global_load_dwordx4 v[152:155], v[126:127], off
	global_load_dwordx4 v[156:159], v[132:133], off
	v_lshlrev_b64 v[126:127], 5, v[168:169]
	v_lshl_add_u64 v[126:127], s[6:7], 0, v[126:127]
	global_load_dwordx4 v[160:163], v[126:127], off
	v_lshl_add_u64 v[134:135], v[50:51], 1, v[124:125]
	v_lshl_add_u64 v[124:125], v[54:55], 1, v[124:125]
	global_load_dwordx4 v[136:139], v[134:135], off
	global_load_dwordx4 v[164:167], v[126:127], off offset:16
	s_nop 0
	global_load_dwordx4 v[124:127], v[124:125], off
	v_lshlrev_b64 v[168:169], 12, v[168:169]
	v_lshl_add_u64 v[168:169], s[0:1], 0, v[168:169]
	v_lshl_add_u64 v[132:133], s[20:21], 0, v[48:49]
	v_lshl_add_u64 v[168:169], v[168:169], 0, s[46:47]
	v_lshlrev_b64 v[170:171], 12, v[132:133]
	v_lshl_add_u64 v[168:169], v[168:169], 0, v[0:1]
	v_lshl_add_u64 v[174:175], s[0:1], 0, v[170:171]
	global_load_dwordx4 v[168:171], v[168:169], off offset:2048
	v_lshl_add_u64 v[134:135], s[20:21], 0, v[52:53]
	v_lshlrev_b64 v[132:133], 5, v[132:133]
	v_lshlrev_b64 v[172:173], 12, v[134:135]
	v_lshl_add_u64 v[132:133], s[6:7], 0, v[132:133]
	v_lshl_add_u64 v[180:181], s[0:1], 0, v[172:173]
	v_lshl_add_u64 v[188:189], v[174:175], 0, s[46:47]
	global_load_dwordx4 v[172:175], v[132:133], off
	global_load_dwordx4 v[176:179], v[132:133], off offset:16
	v_lshlrev_b64 v[134:135], 5, v[134:135]
	v_lshl_add_u64 v[134:135], s[6:7], 0, v[134:135]
	v_lshl_add_u64 v[132:133], v[180:181], 0, s[46:47]
	global_load_dwordx4 v[180:183], v[134:135], off
	global_load_dwordx4 v[184:187], v[134:135], off offset:16
	v_lshl_add_u64 v[134:135], v[188:189], 0, v[0:1]
	v_lshl_add_u64 v[132:133], v[132:133], 0, v[0:1]
	global_load_dwordx4 v[188:191], v[134:135], off offset:2048
	s_nop 0
	global_load_dwordx4 v[132:135], v[132:133], off offset:2048
	s_waitcnt vmcnt(0)
; #define LAS __attribute__((address_space(3)))
; __device__ __forceinline__ unsigned pk2(float lo, float hi) { return pg8::cvt_pk_bf16(lo, hi); }
; __device__ __forceinline__ void spatial_phase(const PT& T, int a, LAS unsigned char* lds, int vc) {
;     ...
;         for (int q = 0; q < 4; ++q) { const int j = jq + 32 * q;
;             const float s1 = (p1[q].x + p1[q].y) + (p1[q].z + p1[q].w), s2 = (p2[q].x + p2[q].y) + (p2[q].z + p2[q].w);
;             const float mu = s1 * (1.0f / D); float var = s2 * (1.0f / D) - mu * mu; var = var > 0.f ? var : 0.f; const float rs = __builtin_amdgcn_rsqf(var + EPS);
;             const u32x4 raw = vreg[q];
;             u32x4 o; o.x = pk2((bflo(raw.x) - mu) * rs * g0.x, (bfhi(raw.x) - mu) * rs * g0.y); o.y = pk2((bflo(raw.y) - mu) * rs * g0.z, (bfhi(raw.y) - mu) * rs * g0.w);
;             o.z = pk2((bflo(raw.z) - mu) * rs * g1.x, (bfhi(raw.z) - mu) * rs * g1.y); o.w = pk2((bflo(raw.w) - mu) * rs * g1.z, (bfhi(raw.w) - mu) * rs * g1.w);
;             *(LAS u32x4*)(sV + j * LDW + c8) = o; *(LAS u32x4*)(sW + j * LDW + c8) = wreg[q]; }
.LBB0_797:
	s_add_i32 s10, s4, s16
	s_ashr_i32 s10, s10, 3
	s_ashr_i32 s11, s10, 31
	s_and_b32 s19, s4, 7
	s_lshl_b32 s46, s19, 8
	s_mov_b32 s20, 0x3a800000
	s_lshl_b32 s19, s19, 7
	s_waitcnt vmcnt(8) lgkmcnt(0)
	v_mov_b32_e32 v192, v141
	v_mov_b32_e32 v193, v142
	v_mov_b32_e32 v141, v143
	v_pk_add_f32 v[140:141], v[192:193], v[140:141]
	v_add_f32_e32 v142, v144, v145
	v_add_f32_e32 v144, v146, v147
	v_mov_b32_e32 v143, v140
	v_mov_b32_e32 v145, v141
	v_pk_add_f32 v[140:141], v[142:143], v[144:145]
	v_lshlrev_b32_e32 v146, 16, v148
	v_pk_mul_f32 v[142:143], v[140:141], s[20:21] op_sel_hi:[1,0]
	v_and_b32_e32 v147, 0xffff0000, v148
	v_fma_f32 v140, -v143, v143, v142
	v_max_f32_e32 v140, 0, v140
	v_add_f32_e32 v140, 0x358637bd, v140
	v_rsq_f32_e32 v145, v140
	v_lshlrev_b32_e32 v148, 16, v149
	v_lshlrev_b32_e32 v73, 16, v150
	v_and_b32_e32 v149, 0xffff0000, v149
	v_and_b32_e32 v150, 0xffff0000, v150
	v_sub_f32_e32 v141, v146, v143
	v_sub_f32_e32 v142, v147, v143
	v_sub_f32_e32 v144, v148, v143
	v_sub_f32_e32 v146, v73, v143
	v_sub_f32_e32 v140, v149, v143
	v_sub_f32_e32 v147, v150, v143
	v_mul_f32_e32 v141, v141, v145
	v_mul_f32_e32 v142, v142, v145
	v_mul_f32_e32 v144, v144, v145
	v_mul_f32_e32 v146, v146, v145
	v_mul_f32_e32 v140, v140, v145
	v_mul_f32_e32 v147, v147, v145
	v_mul_f32_e32 v141, v141, v128
	v_mul_f32_e32 v142, v142, v129
	v_mul_f32_e32 v144, v144, v130
	v_mul_f32_e32 v146, v146, v120
	v_mul_f32_e32 v148, v140, v131
	v_mul_f32_e32 v147, v147, v121
	v_cvt_pk_bf16_f32 v140, v141, v142
	v_cvt_pk_bf16_f32 v141, v144, v148
	v_cvt_pk_bf16_f32 v142, v146, v147
	v_lshlrev_b32_e32 v144, 16, v151
	v_and_b32_e32 v146, 0xffff0000, v151
	v_sub_f32_e32 v144, v144, v143
	v_sub_f32_e32 v143, v146, v143
	v_mul_f32_e32 v143, v143, v145
	v_mul_f32_e32 v144, v144, v145
	v_mul_f32_e32 v143, v143, v123
	v_mul_f32_e32 v144, v144, v122
	v_cvt_pk_bf16_f32 v143, v144, v143
	ds_write_b128 v91, v[140:143] offset:34816
	v_mov_b32_e32 v140, v161
	v_mov_b32_e32 v141, v162
	v_mov_b32_e32 v161, v163
	v_pk_add_f32 v[140:141], v[140:141], v[160:161]
	v_add_f32_e32 v142, v164, v165
	v_add_f32_e32 v144, v166, v167
	v_mov_b32_e32 v143, v140
	v_mov_b32_e32 v145, v141
	v_pk_add_f32 v[140:141], v[142:143], v[144:145]
	ds_write_b128 v91, v[152:155]
	v_pk_mul_f32 v[142:143], v[140:141], s[20:21] op_sel_hi:[1,0]
	v_and_b32_e32 v141, 0xffff0000, v168
	v_fma_f32 v140, -v143, v143, v142
	v_max_f32_e32 v140, 0, v140
	v_add_f32_e32 v140, 0x358637bd, v140
	v_rsq_f32_e32 v144, v140
	v_lshlrev_b32_e32 v140, 16, v168
	v_sub_f32_e32 v140, v140, v143
	v_sub_f32_e32 v141, v141, v143
	v_mul_f32_e32 v140, v140, v144
	v_mul_f32_e32 v141, v141, v144
	v_mul_f32_e32 v140, v128, v140
	v_mul_f32_e32 v141, v129, v141
	v_cvt_pk_bf16_f32 v140, v140, v141
	v_lshlrev_b32_e32 v141, 16, v169
	v_and_b32_e32 v142, 0xffff0000, v169
	v_sub_f32_e32 v141, v141, v143
	v_sub_f32_e32 v142, v142, v143
	v_mul_f32_e32 v141, v141, v144
	v_mul_f32_e32 v142, v142, v144
	v_mul_f32_e32 v141, v130, v141
	v_mul_f32_e32 v142, v131, v142
	v_cvt_pk_bf16_f32 v141, v141, v142
	v_lshlrev_b32_e32 v142, 16, v170
	v_and_b32_e32 v145, 0xffff0000, v170
	v_sub_f32_e32 v142, v142, v143
	v_sub_f32_e32 v145, v145, v143
	v_mul_f32_e32 v142, v142, v144
	v_mul_f32_e32 v145, v145, v144
	v_mul_f32_e32 v142, v142, v120
	v_mul_f32_e32 v145, v145, v121
	v_cvt_pk_bf16_f32 v142, v142, v145
	v_lshlrev_b32_e32 v145, 16, v171
	v_and_b32_e32 v146, 0xffff0000, v171
	v_sub_f32_e32 v145, v145, v143
	v_sub_f32_e32 v143, v146, v143
	v_mul_f32_e32 v143, v143, v144
	v_mul_f32_e32 v145, v145, v144
	v_mul_f32_e32 v143, v143, v123
	v_mul_f32_e32 v145, v145, v122
	v_cvt_pk_bf16_f32 v143, v145, v143
	ds_write_b128 v91, v[140:143] offset:43520
	v_mov_b32_e32 v140, v173
	v_mov_b32_e32 v141, v174
	v_mov_b32_e32 v173, v175
	v_pk_add_f32 v[140:141], v[140:141], v[172:173]
	v_add_f32_e32 v142, v176, v177
	v_add_f32_e32 v144, v178, v179
	v_mov_b32_e32 v143, v140
	v_mov_b32_e32 v145, v141
	v_pk_add_f32 v[140:141], v[142:143], v[144:145]
	ds_write_b128 v91, v[156:159] offset:8704
	v_pk_mul_f32 v[142:143], v[140:141], s[20:21] op_sel_hi:[1,0]
	v_and_b32_e32 v141, 0xffff0000, v188
	v_fma_f32 v140, -v143, v143, v142
	v_max_f32_e32 v140, 0, v140
	v_add_f32_e32 v140, 0x358637bd, v140
	v_rsq_f32_e32 v144, v140
	v_lshlrev_b32_e32 v140, 16, v188
	v_sub_f32_e32 v140, v140, v143
	v_sub_f32_e32 v141, v141, v143
	v_mul_f32_e32 v140, v140, v144
	v_mul_f32_e32 v141, v141, v144
	v_mul_f32_e32 v140, v128, v140
	v_mul_f32_e32 v141, v129, v141
	v_cvt_pk_bf16_f32 v140, v140, v141
	v_lshlrev_b32_e32 v141, 16, v189
	v_and_b32_e32 v142, 0xffff0000, v189
	v_sub_f32_e32 v141, v141, v143
	v_sub_f32_e32 v142, v142, v143
	v_mul_f32_e32 v141, v141, v144
	v_mul_f32_e32 v142, v142, v144
	v_mul_f32_e32 v141, v130, v141
	v_mul_f32_e32 v142, v131, v142
	v_cvt_pk_bf16_f32 v141, v141, v142
	v_lshlrev_b32_e32 v142, 16, v190
	v_and_b32_e32 v145, 0xffff0000, v190
	v_sub_f32_e32 v142, v142, v143
	v_sub_f32_e32 v145, v145, v143
	v_mul_f32_e32 v142, v142, v144
	v_mul_f32_e32 v145, v145, v144
	v_mul_f32_e32 v142, v120, v142
	v_mul_f32_e32 v145, v121, v145
	v_cvt_pk_bf16_f32 v142, v142, v145
	v_lshlrev_b32_e32 v145, 16, v191
	v_and_b32_e32 v146, 0xffff0000, v191
	v_sub_f32_e32 v145, v145, v143
	v_sub_f32_e32 v143, v146, v143
	v_mul_f32_e32 v143, v143, v144
	v_mul_f32_e32 v145, v145, v144
	v_mul_f32_e32 v143, v123, v143
	v_mul_f32_e32 v145, v122, v145
	v_cvt_pk_bf16_f32 v143, v145, v143
	ds_write_b128 v91, v[140:143] offset:52224
	v_mov_b32_e32 v140, v181
	v_mov_b32_e32 v141, v182
	v_mov_b32_e32 v181, v183
	v_pk_add_f32 v[140:141], v[140:141], v[180:181]
	v_add_f32_e32 v142, v184, v185
; #define LAS __attribute__((address_space(3)))
; __device__ __forceinline__ unsigned pk2(float lo, float hi) { return pg8::cvt_pk_bf16(lo, hi); }
; __device__ __forceinline__ void spatial_phase(const PT& T, int a, LAS unsigned char* lds, int vc) {
;     ...
;         for (int q = 0; q < 4; ++q) { const int j = jq + 32 * q; const size_t row = (size_t)nb * 128 + j;
;             wreg[q] = *(const u32x4*)(Wm + (size_t)g * 16384 + j * 128 + c8);
;             vreg[q] = *(const u32x4*)(Z + row * 2048 + 1024 + g * 128 + c8);
;             p1[q] = *(const f32x4*)(vst + 8 * row); p2[q] = *(const f32x4*)(vst + 8 * row + 4); }
;         const f32x4 g0 = *(const f32x4*)(gv + g * 128 + c8), g1 = *(const f32x4*)(gv + g * 128 + c8 + 4);
;     ...
;             const float s1 = (p1[q].x + p1[q].y) + (p1[q].z + p1[q].w), s2 = (p2[q].x + p2[q].y) + (p2[q].z + p2[q].w);
;             const float mu = s1 * (1.0f / D); float var = s2 * (1.0f / D) - mu * mu; var = var > 0.f ? var : 0.f; const float rs = __builtin_amdgcn_rsqf(var + EPS);
;             const u32x4 raw = vreg[q];
;             u32x4 o; o.x = pk2((bflo(raw.x) - mu) * rs * g0.x, (bfhi(raw.x) - mu) * rs * g0.y); o.y = pk2((bflo(raw.y) - mu) * rs * g0.z, (bfhi(raw.y) - mu) * rs * g0.w);
;             o.z = pk2((bflo(raw.z) - mu) * rs * g1.x, (bfhi(raw.z) - mu) * rs * g1.y); o.w = pk2((bflo(raw.w) - mu) * rs * g1.z, (bfhi(raw.w) - mu) * rs * g1.w);
;             *(LAS u32x4*)(sV + j * LDW + c8) = o; *(LAS u32x4*)(sW + j * LDW + c8) = wreg[q]; }
;         u32x2 uu[4][2]; float bsv[4];
; #pragma unroll
;         for (int mt = 0; mt < 4; ++mt) { const int i = ib + 16 * mt + fr; bsv[mt] = bs[g * 128 + i];
; #pragma unroll
;             for (int n = 0; n < 2; ++n) uu[mt][n] = *(const u32x2*)(Z + ((size_t)nb * 128 + i) * 2048 + g * 128 + cb + 16 * n + 4 * fq); }
;         __syncthreads();
;         f32x4 acc[4][2];
; #pragma unroll
;         for (int mt = 0; mt < 4; ++mt)
; #pragma unroll
;             for (int n = 0; n < 2; ++n) acc[mt][n] = (f32x4){0.f, 0.f, 0.f, 0.f};
	v_add_f32_e32 v144, v186, v187
	v_mov_b32_e32 v143, v140
	v_mov_b32_e32 v145, v141
	v_pk_add_f32 v[140:141], v[142:143], v[144:145]
	ds_write_b128 v91, v[136:139] offset:17408
	v_pk_mul_f32 v[140:141], v[140:141], s[20:21] op_sel_hi:[1,0]
	v_lshlrev_b32_e32 v136, 16, v132
	v_fma_f32 v140, -v141, v141, v140
	v_max_f32_e32 v140, 0, v140
	v_add_f32_e32 v140, 0x358637bd, v140
	v_rsq_f32_e32 v140, v140
	v_and_b32_e32 v132, 0xffff0000, v132
	v_sub_f32_e32 v136, v136, v141
	v_sub_f32_e32 v132, v132, v141
	v_mul_f32_e32 v136, v136, v140
	v_mul_f32_e32 v132, v132, v140
	v_mul_f32_e32 v128, v128, v136
	v_mul_f32_e32 v129, v129, v132
	v_cvt_pk_bf16_f32 v128, v128, v129
	v_lshlrev_b32_e32 v129, 16, v133
	v_sub_f32_e32 v129, v129, v141
	v_mul_f32_e32 v129, v129, v140
	v_mul_f32_e32 v129, v130, v129
	v_and_b32_e32 v130, 0xffff0000, v133
	v_sub_f32_e32 v130, v130, v141
	v_mul_f32_e32 v130, v130, v140
	v_mul_f32_e32 v130, v131, v130
	v_cvt_pk_bf16_f32 v129, v129, v130
	v_lshlrev_b32_e32 v130, 16, v134
	v_sub_f32_e32 v130, v130, v141
	v_mul_f32_e32 v130, v130, v140
	v_mul_f32_e32 v120, v120, v130
	v_and_b32_e32 v130, 0xffff0000, v134
	v_sub_f32_e32 v130, v130, v141
	s_lshl_b64 s[20:21], s[10:11], 19
	v_mul_f32_e32 v130, v130, v140
	s_add_u32 s20, s0, s20
	v_mul_f32_e32 v121, v121, v130
	s_addc_u32 s21, s1, s21
	v_cvt_pk_bf16_f32 v130, v120, v121
	v_lshlrev_b32_e32 v120, 16, v135
	v_and_b32_e32 v121, 0xffff0000, v135
	s_add_u32 s20, s20, s46
	v_sub_f32_e32 v120, v120, v141
	v_sub_f32_e32 v121, v121, v141
	s_addc_u32 s21, s21, 0
	v_mul_f32_e32 v120, v120, v140
	v_mul_f32_e32 v121, v121, v140
	s_add_u32 s20, s20, s18
	v_mul_f32_e32 v120, v122, v120
	v_mul_f32_e32 v121, v123, v121
	s_addc_u32 s21, s21, 0
	v_mov_b32_e32 v73, v1
	v_cvt_pk_bf16_f32 v131, v120, v121
	ds_write_b128 v91, v[128:131] offset:60928
	ds_write_b128 v91, v[124:127] offset:26112
	v_lshl_add_u64 v[2:3], s[20:21], 0, v[72:73]
	v_add_u32_e32 v4, s19, v40
	v_ashrrev_i32_e32 v5, 31, v4
	v_lshl_add_u64 v[6:7], v[2:3], 0, v[56:57]
	v_lshl_add_u64 v[4:5], v[4:5], 2, s[8:9]
	v_lshl_add_u64 v[8:9], v[2:3], 0, v[58:59]
	global_load_dwordx2 v[88:89], v[6:7], off
	global_load_dwordx2 v[86:87], v[6:7], off offset:32
	global_load_dwordx2 v[84:85], v[8:9], off
	global_load_dwordx2 v[82:83], v[8:9], off offset:32
	v_lshl_add_u64 v[6:7], v[2:3], 0, v[60:61]
	global_load_dword v95, v[4:5], off
	global_load_dword v94, v[4:5], off offset:64
	global_load_dword v93, v[4:5], off offset:128
	global_load_dword v73, v[4:5], off offset:192
	v_lshl_add_u64 v[2:3], v[2:3], 0, v[62:63]
	global_load_dwordx2 v[80:81], v[6:7], off
	global_load_dwordx2 v[78:79], v[6:7], off offset:32
	global_load_dwordx2 v[76:77], v[2:3], off
	global_load_dwordx2 v[74:75], v[2:3], off offset:32
	v_mov_b32_e32 v2, 0
	v_mov_b32_e32 v96, v92
	v_mov_b32_e32 v97, v41
	s_mov_b32 s20, s17
	v_mov_b32_e32 v3, v2
	v_mov_b32_e32 v4, v2
	v_mov_b32_e32 v5, v2
	v_mov_b32_e32 v6, v2
	v_mov_b32_e32 v7, v2
	v_mov_b32_e32 v8, v2
	v_mov_b32_e32 v9, v2
	v_mov_b32_e32 v10, v2
	v_mov_b32_e32 v11, v2
	v_mov_b32_e32 v12, v2
	v_mov_b32_e32 v13, v2
	v_mov_b32_e32 v14, v2
	v_mov_b32_e32 v15, v2
	v_mov_b32_e32 v16, v2
	v_mov_b32_e32 v17, v2
	v_mov_b32_e32 v18, v2
	v_mov_b32_e32 v19, v2
	v_mov_b32_e32 v20, v2
	v_mov_b32_e32 v21, v2
	v_mov_b32_e32 v22, v2
	v_mov_b32_e32 v23, v2
	v_mov_b32_e32 v24, v2
	v_mov_b32_e32 v25, v2
	v_mov_b32_e32 v26, v2
	v_mov_b32_e32 v27, v2
	v_mov_b32_e32 v28, v2
	v_mov_b32_e32 v29, v2
	v_mov_b32_e32 v30, v2
	v_mov_b32_e32 v31, v2
	v_mov_b32_e32 v32, v2
	v_mov_b32_e32 v33, v2
	s_waitcnt lgkmcnt(0)
	s_barrier
	s_add_i32 s24, s4, s15
	s_cmpk_gt_i32 s24, 0xff
	s_cbranch_scc1 .Lsp_nopf
	s_mov_b32 vcc_hi, 0
	s_add_i32 s26, s24, s16
	s_ashr_i32 s28, s26, 3
	s_ashr_i32 s29, s28, 31
	s_lshl_b64 s[28:29], s[28:29], 7
	v_lshl_add_u64 v[120:121], s[28:29], 0, v[34:35]
	v_lshlrev_b64 v[122:123], 5, v[120:121]
	v_lshl_add_u64 v[122:123], s[6:7], 0, v[122:123]
	global_load_dwordx4 v[140:143], v[122:123], off
	global_load_dwordx4 v[144:147], v[122:123], off offset:16
	s_and_b32 s25, s24, 7
	s_lshl_b32 vcc_lo, s25, 15
	v_lshlrev_b64 v[120:121], 12, v[120:121]
	v_lshl_add_u64 v[124:125], v[36:37], 0, vcc
	v_lshl_add_u64 v[120:121], s[0:1], 0, v[120:121]
	s_lshl_b32 vcc_lo, s25, 8
	v_lshl_add_u64 v[120:121], v[120:121], 0, vcc
	v_lshl_add_u64 v[120:121], v[120:121], 0, v[0:1]
	global_load_dwordx4 v[148:151], v[120:121], off offset:2048
	s_lshl_b32 vcc_lo, s25, 9
	v_lshl_add_u64 v[120:121], v[38:39], 0, vcc
	s_lshl_b32 vcc_lo, s25, 8
	global_load_dwordx4 v[128:131], v[120:121], off
	s_nop 0
	global_load_dwordx4 v[120:123], v[120:121], off offset:16
	v_lshl_add_u64 v[126:127], v[42:43], 1, v[124:125]
	v_lshl_add_u64 v[132:133], v[46:47], 1, v[124:125]
	v_lshl_add_u64 v[168:169], s[28:29], 0, v[44:45]
	global_load_dwordx4 v[152:155], v[126:127], off
	global_load_dwordx4 v[156:159], v[132:133], off
	v_lshlrev_b64 v[126:127], 5, v[168:169]
	v_lshl_add_u64 v[126:127], s[6:7], 0, v[126:127]
	global_load_dwordx4 v[160:163], v[126:127], off
	v_lshl_add_u64 v[134:135], v[50:51], 1, v[124:125]
	v_lshl_add_u64 v[124:125], v[54:55], 1, v[124:125]
	global_load_dwordx4 v[136:139], v[134:135], off
	global_load_dwordx4 v[164:167], v[126:127], off offset:16
	s_nop 0
	global_load_dwordx4 v[124:127], v[124:125], off
	v_lshlrev_b64 v[168:169], 12, v[168:169]
	v_lshl_add_u64 v[168:169], s[0:1], 0, v[168:169]
	v_lshl_add_u64 v[132:133], s[28:29], 0, v[48:49]
	v_lshl_add_u64 v[168:169], v[168:169], 0, vcc
	v_lshlrev_b64 v[170:171], 12, v[132:133]
	v_lshl_add_u64 v[168:169], v[168:169], 0, v[0:1]
	v_lshl_add_u64 v[174:175], s[0:1], 0, v[170:171]
	global_load_dwordx4 v[168:171], v[168:169], off offset:2048
	v_lshl_add_u64 v[134:135], s[28:29], 0, v[52:53]
	v_lshlrev_b64 v[132:133], 5, v[132:133]
	v_lshlrev_b64 v[172:173], 12, v[134:135]
	v_lshl_add_u64 v[132:133], s[6:7], 0, v[132:133]
	v_lshl_add_u64 v[180:181], s[0:1], 0, v[172:173]
	v_lshl_add_u64 v[188:189], v[174:175], 0, vcc
	global_load_dwordx4 v[172:175], v[132:133], off
	global_load_dwordx4 v[176:179], v[132:133], off offset:16
	v_lshlrev_b64 v[134:135], 5, v[134:135]
	v_lshl_add_u64 v[134:135], s[6:7], 0, v[134:135]
	v_lshl_add_u64 v[132:133], v[180:181], 0, vcc
	global_load_dwordx4 v[180:183], v[134:135], off
	global_load_dwordx4 v[184:187], v[134:135], off offset:16
	v_lshl_add_u64 v[134:135], v[188:189], 0, v[0:1]
	v_lshl_add_u64 v[132:133], v[132:133], 0, v[0:1]
	global_load_dwordx4 v[188:191], v[134:135], off offset:2048
	s_nop 0
	global_load_dwordx4 v[132:135], v[132:133], off offset:2048
